# k10 + weight conversion time-split three ways: 1/4 of WGs convert at attention-phase start, 1/2 right after their first differential item, 1/4 between the queues
# baseline (speedup 1.0000x reference)
.LBB0_261:
	s_add_u32 s28, s18, 0x1000000
	s_addc_u32 s29, s19, 0
	s_add_u32 s34, s18, 0x11000000
	s_addc_u32 s35, s19, 0
	s_add_u32 s36, s18, 0x3e000000
	s_addc_u32 s37, s19, 0
	s_add_u32 s12, s18, 0x9000000
	s_addc_u32 s13, s19, 0
	s_add_u32 s38, s18, 0x3dc00000
	s_addc_u32 s39, s19, 0
	s_mov_b32 s4, 1
	s_cmp_eq_u32 s4, 0
	s_cbranch_scc1 .LBB0_667
	s_bfe_u32 s4, s2, 0x20003
	s_cmp_lg_u32 s4, 0
	s_cselect_b64 s[42:43], -1, 0
	s_mov_b32 s101, 0
	s_cmp_eq_u32 s4, 3
	s_cbranch_scc1 .Lgrp_done
	s_cmp_eq_u32 s4, 0
	s_cbranch_scc1 .Lgrp_done
	s_mov_b32 s101, 3
.Lgrp_done:
	s_lshl_b32 s6, s2, 8
	s_cmp_eq_u32 s4, 0
	s_cbranch_scc1 .LBB0_264
	s_ashr_i32 s4, s2, 31
	s_lshr_b32 s4, s4, 29
	s_add_i32 s4, s2, s4
	s_lshr_b32 s4, s4, 3
	s_mulk_i32 s4, 0xf808
	s_add_i32 s62, s4, s6
	s_cbranch_execz .LBB0_265
	s_branch .LBB0_381

.LBB0_410:
	v_lshl_add_u64 v[8:9], s[54:55], 0, v[184:185]
	v_add_co_u32_e32 v20, vcc, 0x13000000, v8
	s_mov_b32 s4, 0x13002000
	s_nop 0
	v_addc_co_u32_e32 v21, vcc, 0, v9, vcc
	v_add_co_u32_e32 v30, vcc, 0x39300000, v8
	global_load_dwordx2 v[20:21], v[20:21], off
	s_nop 0
	v_addc_co_u32_e32 v31, vcc, 0, v9, vcc
	global_load_dwordx2 v[30:31], v[30:31], off
	v_add_co_u32_e64 v22, s[4:5], s4, v8
	v_lshl_add_u64 v[6:7], s[52:53], 0, v[184:185]
	s_nop 0
	v_addc_co_u32_e64 v23, s[4:5], 0, v9, s[4:5]
	v_add_co_u32_e64 v24, s[4:5], s78, v8
	s_movk_i32 s7, 0x2000
	s_nop 0
	v_addc_co_u32_e64 v25, s[4:5], 0, v9, s[4:5]
	v_add_co_u32_e64 v26, s[4:5], s7, v6
	s_add_i32 s6, s50, s56
	s_nop 0
	v_addc_co_u32_e64 v27, s[4:5], 0, v7, s[4:5]
	v_add_co_u32_e64 v10, s[4:5], s79, v8
	s_and_b32 s44, s6, 0xfc
	s_nop 0
	v_addc_co_u32_e64 v11, s[4:5], 0, v9, s[4:5]
	v_add_co_u32_e64 v28, s[4:5], s80, v8
	s_add_i32 s14, s6, 2
	s_or_b64 s[6:7], s[44:45], s[48:49]
	s_lshl_b64 s[6:7], s[6:7], 13
	v_lshl_add_u64 v[32:33], v[0:1], 0, s[6:7]
	s_mov_b32 s59, s49
	s_waitcnt vmcnt(1)
	v_lshlrev_b32_e32 v8, 16, v20
	v_and_b32_e32 v19, 0xffff0000, v20
	v_alignbit_b32 v20, v21, v20, 16
	v_and_b32_e32 v29, 0xffff0000, v21
	s_waitcnt vmcnt(0)
	v_lshlrev_b32_e32 v21, 16, v30
	v_and_b32_e32 v34, 0xffff0000, v30
	v_alignbit_b32 v30, v31, v30, 16
	v_and_b32_e32 v31, 0xffff0000, v31
	v_and_b32_e32 v35, 0xffff0000, v20
	v_fma_f32 v20, -v18, v21, v8
	v_fma_f32 v21, -v18, v34, v19
	v_and_b32_e32 v8, 0xffff0000, v30
	v_fma_f32 v31, -v18, v31, v29
	v_fma_f32 v30, -v18, v8, v35
	v_mul_f32_e32 v8, v21, v21
	v_mul_f32_e32 v19, v31, v31
	v_fmac_f32_e32 v8, v20, v20
	v_fmac_f32_e32 v19, v30, v30
	v_add_f32_e32 v8, v8, v19
	ds_bpermute_b32 v19, v12, v8
	s_waitcnt lgkmcnt(0)
	v_add_f32_e32 v8, v8, v19
	ds_bpermute_b32 v19, v13, v8
	s_waitcnt lgkmcnt(0)
	v_add_f32_e32 v8, v8, v19
	ds_bpermute_b32 v19, v14, v8
	s_waitcnt lgkmcnt(0)
	v_add_f32_e32 v8, v8, v19
	ds_bpermute_b32 v19, v15, v8
	s_waitcnt lgkmcnt(0)
	v_add_f32_e32 v8, v8, v19
	ds_bpermute_b32 v19, v16, v8
	s_waitcnt lgkmcnt(0)
	v_add_f32_e32 v8, v8, v19
	ds_bpermute_b32 v19, v17, v8
	s_waitcnt lgkmcnt(0)
	v_add_f32_e32 v8, v8, v19
	v_fmamk_f32 v8, v8, 0x3b800000, v191
	v_mul_f32_e32 v19, 0x4f800000, v8
	v_cmp_gt_f32_e32 vcc, s76, v8
	s_nop 1
	v_cndmask_b32_e32 v8, v8, v19, vcc
	v_sqrt_f32_e32 v19, v8
	s_nop 0
	v_add_u32_e32 v29, -1, v19
	v_add_u32_e32 v34, 1, v19
	v_fma_f32 v35, -v29, v19, v8
	v_fma_f32 v36, -v34, v19, v8
	v_cmp_ge_f32_e64 s[6:7], 0, v35
	s_nop 1
	v_cndmask_b32_e64 v19, v19, v29, s[6:7]
	v_cmp_lt_f32_e64 s[6:7], 0, v36
	s_nop 1
	v_cndmask_b32_e64 v19, v19, v34, s[6:7]
	v_mul_f32_e32 v29, 0x37800000, v19
	v_cndmask_b32_e32 v19, v19, v29, vcc
	v_cmp_class_f32_e32 vcc, v8, v192
	s_nop 1
	v_cndmask_b32_e32 v8, v19, v8, vcc
	v_div_scale_f32 v19, s[6:7], v8, v8, 1.0
	v_rcp_f32_e32 v34, v19
	v_div_scale_f32 v29, vcc, 1.0, v8, 1.0
	v_fma_f32 v35, -v19, v34, 1.0
	v_fmac_f32_e32 v34, v35, v34
	v_mul_f32_e32 v35, v29, v34
	v_fma_f32 v36, -v19, v35, v29
	v_fmac_f32_e32 v35, v36, v34
	v_fma_f32 v19, -v19, v35, v29
	v_div_fmas_f32 v19, v19, v34, v35
	v_div_fixup_f32 v8, v19, v8, 1.0
	v_pk_mul_f32 v[20:21], v[20:21], v[8:9] op_sel_hi:[1,0]
	v_pk_mul_f32 v[30:31], v[30:31], v[8:9] op_sel_hi:[1,0]
	v_pk_mul_f32 v[20:21], v[4:5], v[20:21]
	v_pk_mul_f32 v[30:31], v[2:3], v[30:31]
	v_bfe_u32 v8, v20, 16, 1
	v_bfe_u32 v29, v30, 16, 1
	v_bfe_u32 v19, v21, 16, 1
	v_bfe_u32 v34, v31, 16, 1
	v_add3_u32 v8, v20, v8, s77
	v_add3_u32 v20, v30, v29, s77
	v_add3_u32 v19, v21, v19, s77
	v_add3_u32 v21, v31, v34, s77
	v_lshrrev_b32_e32 v8, 16, v8
	v_lshrrev_b32_e32 v29, 16, v20
	v_and_or_b32 v20, v19, s75, v8
	v_and_or_b32 v21, v21, s75, v29
	global_store_dwordx2 v[32:33], v[20:21], off
	global_load_dwordx2 v[20:21], v[22:23], off offset:-4096
	s_nop 0
	global_load_dwordx2 v[30:31], v[24:25], off offset:-4096
	s_waitcnt vmcnt(1)
	v_lshlrev_b32_e32 v8, 16, v20
	s_waitcnt vmcnt(0)
	v_lshlrev_b32_e32 v19, 16, v30
	v_and_b32_e32 v29, 0xffff0000, v20
	v_and_b32_e32 v32, 0xffff0000, v30
	v_alignbit_b32 v33, v21, v20, 16
	v_alignbit_b32 v30, v31, v30, 16
	v_and_b32_e32 v34, 0xffff0000, v21
	v_and_b32_e32 v31, 0xffff0000, v31
	v_fma_f32 v20, -v18, v19, v8
	v_fma_f32 v21, -v18, v32, v29
	v_and_b32_e32 v8, 0xffff0000, v33
	v_and_b32_e32 v19, 0xffff0000, v30
	v_fma_f32 v31, -v18, v31, v34
	v_fma_f32 v30, -v18, v19, v8
	v_mul_f32_e32 v8, v21, v21
	v_mul_f32_e32 v19, v31, v31
	v_fmac_f32_e32 v8, v20, v20
	v_fmac_f32_e32 v19, v30, v30
	v_add_f32_e32 v8, v8, v19
	ds_bpermute_b32 v19, v12, v8
	s_waitcnt lgkmcnt(0)
	v_add_f32_e32 v8, v8, v19
	ds_bpermute_b32 v19, v13, v8
	s_waitcnt lgkmcnt(0)
	v_add_f32_e32 v8, v8, v19
	ds_bpermute_b32 v19, v14, v8
	s_waitcnt lgkmcnt(0)
	v_add_f32_e32 v8, v8, v19
	ds_bpermute_b32 v19, v15, v8
	s_waitcnt lgkmcnt(0)
	v_add_f32_e32 v8, v8, v19
	ds_bpermute_b32 v19, v16, v8
	s_waitcnt lgkmcnt(0)
	v_add_f32_e32 v8, v8, v19
	ds_bpermute_b32 v19, v17, v8
	s_waitcnt lgkmcnt(0)
	v_add_f32_e32 v8, v8, v19
	v_fmamk_f32 v8, v8, 0x3b800000, v191
	v_mul_f32_e32 v19, 0x4f800000, v8
	v_cmp_gt_f32_e32 vcc, s76, v8
	s_nop 1
	v_cndmask_b32_e32 v8, v8, v19, vcc
	v_sqrt_f32_e32 v19, v8
	s_nop 0
	v_add_u32_e32 v29, -1, v19
	v_add_u32_e32 v32, 1, v19
	v_fma_f32 v33, -v29, v19, v8
	v_fma_f32 v34, -v32, v19, v8
	v_cmp_ge_f32_e64 s[6:7], 0, v33
	s_nop 1
	v_cndmask_b32_e64 v19, v19, v29, s[6:7]
	v_cmp_lt_f32_e64 s[6:7], 0, v34
	s_nop 1
	v_cndmask_b32_e64 v19, v19, v32, s[6:7]
	v_mul_f32_e32 v29, 0x37800000, v19
	v_cndmask_b32_e32 v19, v19, v29, vcc
	v_cmp_class_f32_e32 vcc, v8, v192
	s_nop 1
	v_cndmask_b32_e32 v8, v19, v8, vcc
	v_div_scale_f32 v19, s[6:7], v8, v8, 1.0
	v_rcp_f32_e32 v32, v19
	v_div_scale_f32 v29, vcc, 1.0, v8, 1.0
	v_fma_f32 v33, -v19, v32, 1.0
	v_fmac_f32_e32 v32, v33, v32
	v_mul_f32_e32 v33, v29, v32
	v_fma_f32 v34, -v19, v33, v29
	v_fmac_f32_e32 v33, v34, v32
	v_fma_f32 v19, -v19, v33, v29
	v_div_fmas_f32 v19, v19, v32, v33
	v_div_fixup_f32 v8, v19, v8, 1.0
	v_pk_mul_f32 v[20:21], v[20:21], v[8:9] op_sel_hi:[1,0]
	v_pk_mul_f32 v[30:31], v[30:31], v[8:9] op_sel_hi:[1,0]
	v_pk_mul_f32 v[20:21], v[4:5], v[20:21]
	v_pk_mul_f32 v[30:31], v[2:3], v[30:31]
	v_bfe_u32 v8, v20, 16, 1
	v_bfe_u32 v29, v30, 16, 1
	v_bfe_u32 v19, v21, 16, 1
	v_bfe_u32 v32, v31, 16, 1
	v_add3_u32 v8, v20, v8, s77
	v_add3_u32 v20, v30, v29, s77
	v_add3_u32 v19, v21, v19, s77
	v_add3_u32 v21, v31, v32, s77
	v_lshrrev_b32_e32 v8, 16, v8
	v_lshrrev_b32_e32 v29, 16, v20
	v_and_or_b32 v20, v19, s75, v8
	v_and_or_b32 v21, v21, s75, v29
	global_store_dwordx2 v[26:27], v[20:21], off
	global_load_dwordx2 v[20:21], v[22:23], off
	s_nop 0
	global_load_dwordx2 v[22:23], v[24:25], off
	v_addc_co_u32_e64 v29, vcc, 0, v9, s[4:5]
	s_and_b32 s4, s14, 0xfe
	s_or_b32 s58, s48, s4
	s_lshl_b64 s[4:5], s[58:59], 13
	v_lshl_add_u64 v[8:9], v[0:1], 0, s[4:5]
	s_add_u32 s52, s52, 0x8000
	s_addc_u32 s53, s53, 0
	s_add_u32 s54, s54, 0x4000
	s_addc_u32 s55, s55, 0
	s_add_u32 s56, s56, 4
	s_addc_u32 s57, s57, 0
	s_cmp_eq_u32 s56, 32
	s_waitcnt vmcnt(1)
	v_lshlrev_b32_e32 v19, 16, v20
	s_waitcnt vmcnt(0)
	v_lshlrev_b32_e32 v24, 16, v22
	v_and_b32_e32 v25, 0xffff0000, v20
	v_and_b32_e32 v26, 0xffff0000, v22
	v_alignbit_b32 v27, v21, v20, 16
	v_alignbit_b32 v22, v23, v22, 16
	v_and_b32_e32 v30, 0xffff0000, v21
	v_and_b32_e32 v23, 0xffff0000, v23
	v_fma_f32 v20, -v18, v24, v19
	v_fma_f32 v21, -v18, v26, v25
	v_and_b32_e32 v19, 0xffff0000, v27
	v_and_b32_e32 v22, 0xffff0000, v22
	v_fma_f32 v23, -v18, v23, v30
	v_fma_f32 v22, -v18, v22, v19
	v_mul_f32_e32 v19, v21, v21
	v_mul_f32_e32 v24, v23, v23
	v_fmac_f32_e32 v19, v20, v20
	v_fmac_f32_e32 v24, v22, v22
	v_add_f32_e32 v19, v19, v24
	ds_bpermute_b32 v24, v12, v19
	s_waitcnt lgkmcnt(0)
	v_add_f32_e32 v19, v19, v24
	ds_bpermute_b32 v24, v13, v19
	s_waitcnt lgkmcnt(0)
	v_add_f32_e32 v19, v19, v24
	ds_bpermute_b32 v24, v14, v19
	s_waitcnt lgkmcnt(0)
	v_add_f32_e32 v19, v19, v24
	ds_bpermute_b32 v24, v15, v19
	s_waitcnt lgkmcnt(0)
	v_add_f32_e32 v19, v19, v24
	ds_bpermute_b32 v24, v16, v19
	s_waitcnt lgkmcnt(0)
	v_add_f32_e32 v19, v19, v24
	ds_bpermute_b32 v24, v17, v19
	s_waitcnt lgkmcnt(0)
	v_add_f32_e32 v19, v19, v24
	v_fmamk_f32 v19, v19, 0x3b800000, v191
	v_mul_f32_e32 v24, 0x4f800000, v19
	v_cmp_gt_f32_e32 vcc, s76, v19
	s_nop 1
	v_cndmask_b32_e32 v19, v19, v24, vcc
	v_sqrt_f32_e32 v24, v19
	s_nop 0
	v_add_u32_e32 v25, -1, v24
	v_add_u32_e32 v26, 1, v24
	v_fma_f32 v27, -v25, v24, v19
	v_fma_f32 v30, -v26, v24, v19
	v_cmp_ge_f32_e64 s[4:5], 0, v27
	s_nop 1
	v_cndmask_b32_e64 v24, v24, v25, s[4:5]
	v_cmp_lt_f32_e64 s[4:5], 0, v30
	s_nop 1
	v_cndmask_b32_e64 v24, v24, v26, s[4:5]
	v_mul_f32_e32 v25, 0x37800000, v24
	v_cndmask_b32_e32 v24, v24, v25, vcc
	v_cmp_class_f32_e32 vcc, v19, v192
	s_nop 1
	v_cndmask_b32_e32 v19, v24, v19, vcc
	v_div_scale_f32 v24, s[4:5], v19, v19, 1.0
	v_rcp_f32_e32 v26, v24
	v_div_scale_f32 v25, vcc, 1.0, v19, 1.0
	v_fma_f32 v27, -v24, v26, 1.0
	v_fmac_f32_e32 v26, v27, v26
	v_mul_f32_e32 v27, v25, v26
	v_fma_f32 v30, -v24, v27, v25
	v_fmac_f32_e32 v27, v30, v26
	v_fma_f32 v24, -v24, v27, v25
	v_div_fmas_f32 v24, v24, v26, v27
	v_div_fixup_f32 v24, v24, v19, 1.0
	v_pk_mul_f32 v[20:21], v[20:21], v[24:25] op_sel_hi:[1,0]
	v_pk_mul_f32 v[22:23], v[22:23], v[24:25] op_sel_hi:[1,0]
	v_pk_mul_f32 v[20:21], v[4:5], v[20:21]
	v_pk_mul_f32 v[22:23], v[2:3], v[22:23]
	v_bfe_u32 v19, v20, 16, 1
	v_bfe_u32 v24, v21, 16, 1
	v_bfe_u32 v25, v22, 16, 1
	v_bfe_u32 v26, v23, 16, 1
	v_add3_u32 v19, v20, v19, s77
	v_add3_u32 v20, v21, v24, s77
	v_add3_u32 v21, v22, v25, s77
	v_add3_u32 v22, v23, v26, s77
	v_lshrrev_b32_e32 v19, 16, v19
	v_lshrrev_b32_e32 v21, 16, v21
	v_and_or_b32 v20, v20, s75, v19
	v_and_or_b32 v21, v22, s75, v21
	global_store_dwordx2 v[8:9], v[20:21], off
	global_load_dwordx2 v[8:9], v[10:11], off
	s_nop 0
	global_load_dwordx2 v[10:11], v[28:29], off
	s_waitcnt vmcnt(1)
	v_lshlrev_b32_e32 v19, 16, v8
	s_waitcnt vmcnt(0)
	v_lshlrev_b32_e32 v20, 16, v10
	v_and_b32_e32 v21, 0xffff0000, v8
	v_and_b32_e32 v22, 0xffff0000, v10
	v_alignbit_b32 v23, v9, v8, 16
	v_alignbit_b32 v10, v11, v10, 16
	v_and_b32_e32 v24, 0xffff0000, v9
	v_and_b32_e32 v11, 0xffff0000, v11
	v_fma_f32 v8, -v18, v20, v19
	v_fma_f32 v9, -v18, v22, v21
	v_and_b32_e32 v19, 0xffff0000, v23
	v_and_b32_e32 v10, 0xffff0000, v10
	v_fma_f32 v11, -v18, v11, v24
	v_fma_f32 v10, -v18, v10, v19
	v_mul_f32_e32 v19, v9, v9
	v_mul_f32_e32 v20, v11, v11
	v_fmac_f32_e32 v19, v8, v8
	v_fmac_f32_e32 v20, v10, v10
	v_add_f32_e32 v19, v19, v20
	ds_bpermute_b32 v20, v12, v19
	s_waitcnt lgkmcnt(0)
	v_add_f32_e32 v19, v19, v20
	ds_bpermute_b32 v20, v13, v19
	s_waitcnt lgkmcnt(0)
	v_add_f32_e32 v19, v19, v20
	ds_bpermute_b32 v20, v14, v19
	s_waitcnt lgkmcnt(0)
	v_add_f32_e32 v19, v19, v20
	ds_bpermute_b32 v20, v15, v19
	s_waitcnt lgkmcnt(0)
	v_add_f32_e32 v19, v19, v20
	ds_bpermute_b32 v20, v16, v19
	s_waitcnt lgkmcnt(0)
	v_add_f32_e32 v19, v19, v20
	ds_bpermute_b32 v20, v17, v19
	s_waitcnt lgkmcnt(0)
	v_add_f32_e32 v19, v19, v20
	v_fmamk_f32 v19, v19, 0x3b800000, v191
	v_mul_f32_e32 v20, 0x4f800000, v19
	v_cmp_gt_f32_e32 vcc, s76, v19
	s_nop 1
	v_cndmask_b32_e32 v19, v19, v20, vcc
	v_sqrt_f32_e32 v20, v19
	s_nop 0
	v_add_u32_e32 v21, -1, v20
	v_add_u32_e32 v22, 1, v20
	v_fma_f32 v23, -v21, v20, v19
	v_fma_f32 v24, -v22, v20, v19
	v_cmp_ge_f32_e64 s[4:5], 0, v23
	s_nop 1
	v_cndmask_b32_e64 v20, v20, v21, s[4:5]
	v_cmp_lt_f32_e64 s[4:5], 0, v24
	s_nop 1
	v_cndmask_b32_e64 v20, v20, v22, s[4:5]
	v_mul_f32_e32 v21, 0x37800000, v20
	v_cndmask_b32_e32 v20, v20, v21, vcc
	v_cmp_class_f32_e32 vcc, v19, v192
	s_nop 1
	v_cndmask_b32_e32 v19, v20, v19, vcc
	v_div_scale_f32 v20, s[4:5], v19, v19, 1.0
	v_rcp_f32_e32 v22, v20
	v_div_scale_f32 v21, vcc, 1.0, v19, 1.0
	v_fma_f32 v23, -v20, v22, 1.0
	v_fmac_f32_e32 v22, v23, v22
	v_mul_f32_e32 v23, v21, v22
	v_fma_f32 v24, -v20, v23, v21
	v_fmac_f32_e32 v23, v24, v22
	v_fma_f32 v20, -v20, v23, v21
	v_div_fmas_f32 v20, v20, v22, v23
	v_div_fixup_f32 v20, v20, v19, 1.0
	v_pk_mul_f32 v[8:9], v[8:9], v[20:21] op_sel_hi:[1,0]
	v_pk_mul_f32 v[10:11], v[10:11], v[20:21] op_sel_hi:[1,0]
	v_pk_mul_f32 v[8:9], v[4:5], v[8:9]
	v_pk_mul_f32 v[10:11], v[2:3], v[10:11]
	v_bfe_u32 v19, v8, 16, 1
	v_bfe_u32 v21, v10, 16, 1
	v_bfe_u32 v20, v9, 16, 1
	v_bfe_u32 v22, v11, 16, 1
	v_add3_u32 v8, v8, v19, s77
	v_add3_u32 v10, v10, v21, s77
	v_add_co_u32_e32 v6, vcc, s81, v6
	v_add3_u32 v9, v9, v20, s77
	v_add3_u32 v11, v11, v22, s77
	v_lshrrev_b32_e32 v8, 16, v8
	v_lshrrev_b32_e32 v10, 16, v10
	v_addc_co_u32_e32 v7, vcc, 0, v7, vcc
	v_and_or_b32 v8, v9, s75, v8
	v_and_or_b32 v9, v11, s75, v10
	global_store_dwordx2 v[6:7], v[8:9], off
	s_cbranch_scc0 .LBB0_410
	s_cmp_eq_u32 s101, 3
	s_cbranch_scc0 .Lc3_norm
	s_mov_b32 s101, 1
	s_branch .LBB0_412
.Lc3_norm:
	s_mov_b64 s[4:5], 0
	s_branch .LBB0_386

.LBB0_529:
	s_cmp_eq_u32 s101, 1
	s_cbranch_scc0 .Lc3_fox
	s_mov_b32 s101, 2
	s_mov_b64 s[42:43], 0
	s_mov_b32 s45, 0
	v_readlane_b32 s82, v255, 2
	v_readlane_b32 s83, v255, 3
	s_nop 3
	s_branch .LBB0_383
